# grid barrier: all workgroups poll the top generation word directly (flat release), leader invalidates with its writeback
# speedup vs baseline: 1.0126x; 1.0065x over previous
; __device__ __forceinline__ unsigned xb_ld(unsigned* p)              { return __hip_atomic_load(p, __ATOMIC_RELAXED, __HIP_MEMORY_SCOPE_AGENT); }
; __device__ __forceinline__ unsigned xb_add(unsigned* p, unsigned v) { return __hip_atomic_fetch_add(p, v, __ATOMIC_RELAXED, __HIP_MEMORY_SCOPE_AGENT); }
; #define XB_SPIN(cond, bar) do { unsigned _sp = 0; while (cond) { __builtin_amdgcn_s_sleep(1); \
;     if ((++_sp & 255u) == 0u) { if (xb_ld(&(bar)[XB_TMO])) break; if (_sp > XB_SPIN_CAP) { atomicAdd(&(bar)[XB_TMO], 1u); break; } } } } while (0)
; __device__ __forceinline__ void xcd_barrier(const XcdBarrier& b) {
;     ...
;         const unsigned old = xb_add(&bar[XB_XSUB(b.x)], 1u);
;         const unsigned gen = old / nloc;
;         if (old + 1u == (gen + 1u) * nloc) {
;             __builtin_amdgcn_fence(__ATOMIC_RELEASE, "agent");
;             asm volatile("s_waitcnt vmcnt(0)" ::: "memory");
;             const unsigned og = xb_add(&bar[XB_TOP], 1u);
;             const unsigned tg = og / nx;
;             if (og + 1u == (tg + 1u) * nx) xb_add(&bar[XB_TOPGEN], 1u);
;             else XB_SPIN(xb_ld(&bar[XB_TOPGEN]) == tg, bar);
;             __builtin_amdgcn_fence(__ATOMIC_ACQUIRE, "agent");
;             xb_add(&bar[XB_XGEN(b.x)], 1u);
;             asm volatile("s_waitcnt vmcnt(0)" ::: "memory");
;         } else {
;             XB_SPIN(xb_ld(&bar[XB_XGEN(b.x)]) == gen, bar);
;             __builtin_amdgcn_fence(__ATOMIC_ACQUIRE, "agent");
;             asm volatile("s_waitcnt vmcnt(0)" ::: "memory");
.LBB0_1038:
	s_or_b64 exec, exec, s[6:7]
	v_cvt_f32_u32_e32 v5, v3
	s_waitcnt vmcnt(0)
	v_readfirstlane_b32 s4, v4
	v_sub_u32_e32 v4, 0, v3
	v_rcp_iflag_f32_e32 v5, v5
	v_add_u32_e32 v6, s4, v0
	v_mul_f32_e32 v5, 0x4f7ffffe, v5
	v_cvt_u32_f32_e32 v5, v5
	v_mul_lo_u32 v0, v4, v5
	v_mul_hi_u32 v0, v5, v0
	v_add_u32_e32 v0, v5, v0
	v_mul_hi_u32 v0, v6, v0
	v_mul_lo_u32 v4, v0, v3
	v_sub_u32_e32 v4, v6, v4
	v_add_u32_e32 v5, 1, v0
	v_cmp_ge_u32_e32 vcc, v4, v3
	s_nop 1
	v_cndmask_b32_e32 v0, v0, v5, vcc
	v_sub_u32_e32 v5, v4, v3
	v_cndmask_b32_e32 v4, v4, v5, vcc
	v_add_u32_e32 v5, 1, v0
	v_cmp_ge_u32_e32 vcc, v4, v3
	v_add_u32_e32 v4, 1, v6
	s_nop 0
	v_cndmask_b32_e32 v0, v0, v5, vcc
	v_mul_lo_u32 v5, v3, v0
	v_add_u32_e32 v3, v5, v3
	v_cmp_ne_u32_e32 vcc, v4, v3
	s_and_saveexec_b64 s[4:5], vcc
	s_xor_b64 s[4:5], exec, s[4:5]
	s_cbranch_execz .LBB0_1052
	s_waitcnt lgkmcnt(0)
	buffer_inv sc1
	s_add_u32 s8, s90, 0x3500
	s_addc_u32 s9, s91, 0
	global_load_dword v2, v1, s[8:9] sc1
	s_waitcnt vmcnt(0)
	v_cmp_eq_u32_e32 vcc, v2, v0
	s_and_saveexec_b64 s[6:7], vcc
	s_cbranch_execz .LBB0_1051
	s_mov_b32 s20, 1
	s_mov_b64 s[10:11], 0
	s_branch .LBB0_1042

; __device__ __forceinline__ unsigned xb_add(unsigned* p, unsigned v) { return __hip_atomic_fetch_add(p, v, __ATOMIC_RELAXED, __HIP_MEMORY_SCOPE_AGENT); }
; __device__ __forceinline__ void xcd_barrier(const XcdBarrier& b) {
;     ...
;             __builtin_amdgcn_fence(__ATOMIC_RELEASE, "agent");
;             asm volatile("s_waitcnt vmcnt(0)" ::: "memory");
;             const unsigned og = xb_add(&bar[XB_TOP], 1u);
;             const unsigned tg = og / nx;
.LBB0_1053:
	s_mov_b64 s[4:5], exec
	buffer_wbl2 sc1
	buffer_inv sc1
	s_waitcnt lgkmcnt(0)
	s_waitcnt vmcnt(0)
	v_mbcnt_lo_u32_b32 v0, s4, 0
	v_mbcnt_hi_u32_b32 v0, s5, v0
	v_cmp_eq_u32_e32 vcc, 0, v0
	s_and_saveexec_b64 s[6:7], vcc
	s_cbranch_execz .LBB0_1055
	s_bcnt1_i32_b64 s4, s[4:5]
	v_mov_b32_e32 v3, s4
	v_mov_b32_e32 v4, 0x3000
	global_atomic_add v3, v4, v3, s[90:91] offset:1024 sc0

; __device__ __forceinline__ unsigned xb_ld(unsigned* p)              { return __hip_atomic_load(p, __ATOMIC_RELAXED, __HIP_MEMORY_SCOPE_AGENT); }
; __device__ __forceinline__ unsigned xb_add(unsigned* p, unsigned v) { return __hip_atomic_fetch_add(p, v, __ATOMIC_RELAXED, __HIP_MEMORY_SCOPE_AGENT); }
; #define XB_SPIN(cond, bar) do { unsigned _sp = 0; while (cond) { __builtin_amdgcn_s_sleep(1); \
;     if ((++_sp & 255u) == 0u) { if (xb_ld(&(bar)[XB_TMO])) break; if (_sp > XB_SPIN_CAP) { atomicAdd(&(bar)[XB_TMO], 1u); break; } } } } while (0)
; __device__ __forceinline__ void xcd_barrier(const XcdBarrier& b) {
;     ...
;             if (og + 1u == (tg + 1u) * nx) xb_add(&bar[XB_TOPGEN], 1u);
;             else XB_SPIN(xb_ld(&bar[XB_TOPGEN]) == tg, bar);
;             __builtin_amdgcn_fence(__ATOMIC_ACQUIRE, "agent");
;             xb_add(&bar[XB_XGEN(b.x)], 1u);
.LBB0_1067:
	s_or_b64 exec, exec, s[6:7]
	s_and_saveexec_b64 s[4:5], s[8:9]
	s_cbranch_execz .LBB0_1069
	v_mov_b32_e32 v0, 1
	global_atomic_add v[2:3], v0, off
.LBB0_1069:
	s_or_b64 exec, exec, s[4:5]
	s_mov_b64 s[4:5], exec
	v_mbcnt_lo_u32_b32 v0, s4, 0
	v_mbcnt_hi_u32_b32 v0, s5, v0
	v_cmp_eq_u32_e32 vcc, 0, v0
	s_and_saveexec_b64 s[6:7], vcc
	s_cbranch_execnz .LBB0_1070
	s_getpc_b64 s[98:99]

; __device__ __forceinline__ unsigned xb_add(unsigned* p, unsigned v) { return __hip_atomic_fetch_add(p, v, __ATOMIC_RELAXED, __HIP_MEMORY_SCOPE_AGENT); }
; __device__ __forceinline__ void xcd_barrier(const XcdBarrier& b) {
;     ...
;             xb_add(&bar[XB_XGEN(b.x)], 1u);
;             asm volatile("s_waitcnt vmcnt(0)" ::: "memory");
.LBB0_1070:
	s_bcnt1_i32_b64 s4, s[4:5]
	v_mov_b32_e32 v0, s4
	s_getpc_b64 s[98:99]
